# stage_tile de-serialised at the remaining rs-scaled sites (ph_qkv KV, ph_in, ph_qm): four 128-bit rs reads + paired ds_write2_b32 instead of 64 read-wait-mul-write round trips; paired stage writes at
# speedup vs baseline: 1.0153x; 1.0084x over previous
; DI int tid() { int t = threadIdx.x; asm volatile("" : "+v"(t)); return t; }
; DI int crow(int r, int h) { return (r & 3) + 8 * (r >> 2) + 4 * h; }
; DI void ph_up(KP p, int l, char* smem) {
;     ...
;         rs_finish(rsp, b * SEQ + s0 - 1, smem);
;         const float* rs = (const float*)(smem + RS_OFF);
;         float* stg = (float*)smem;
;         const int tt = tid(), lane = tt & 63, w = __builtin_amdgcn_readfirstlane(tt >> 6), wm = w >> 1, wn = w & 1, l32 = lane & 31, h = lane >> 5;
; #pragma unroll
;         for (int i = 0; i < 2; ++i)
; #pragma unroll
;             for (int j = 0; j < 2; ++j)
; #pragma unroll
;                 for (int r = 0; r < 16; ++r) {
;                     const int row = wm * 64 + i * 32 + crow(r, h), col = wn * 64 + j * 32 + l32;
;                     stg[row * 130 + col] = acc[i][j][r] * rs[row];
;                 }
;         __syncthreads();
;         bf16_t* act = (bf16_t*)(p->ws + OFF_ACT);
;         const int rmax = min(126, SEQ - s0);
;         const int rbeg = w * 32 + h * 16, rend = min(rbeg + 16, rmax);
;         if (rbeg < rend) {
;             const float* sg = stg + rbeg * 130 + cp2;
;             unsigned* arow = (unsigned*)(act + ((size_t)b * SEQ + s0 + rbeg) * DFF + c);
;             f32p ga = *(const f32p*)sg, gm = *(const f32p*)(sg + 130), ua = *(const f32p*)(sg + 64), um = *(const f32p*)(sg + 130 + 64);
.LBB0_79:
	s_or_b64 exec, exec, s[16:17]
	v_mov_b32_e32 v34, v182
	s_waitcnt lgkmcnt(0)
	s_barrier
	s_nop 0
	v_readfirstlane_b32 s12, v34
	s_ashr_i32 s11, s12, 1
	v_bfe_u32 v68, v34, 5, 1
	s_and_b32 s13, s11, 0xffffffc0
	v_lshl_or_b32 v69, v68, 2, s13
	v_lshl_add_u32 v70, v69, 2, 0
	v_add_u32_e32 v70, 0x12000, v70
	ds_read_b128 v[198:201], v70
	ds_read_b128 v[202:205], v70 offset:32
	ds_read_b128 v[206:209], v70 offset:64
	ds_read_b128 v[210:213], v70 offset:96
	v_and_b32_e32 v34, 31, v34
	v_and_or_b32 v34, s12, 64, v34
	s_movk_i32 s12, 0x208
	v_mul_lo_u32 v69, v69, s12
	v_lshlrev_b32_e32 v34, 2, v34
	v_add3_u32 v34, 0, v69, v34
	s_andn2_b32 s11, s11, 31
	s_sub_i32 s12, 0x2000, s10
	s_waitcnt lgkmcnt(0)
	v_mul_f32_e32 v52, v52, v198
	v_mul_f32_e32 v53, v53, v199
	v_mul_f32_e32 v54, v54, v200
	v_mul_f32_e32 v55, v55, v201
	v_mul_f32_e32 v56, v56, v202
	v_mul_f32_e32 v57, v57, v203
	v_mul_f32_e32 v58, v58, v204
	v_mul_f32_e32 v59, v59, v205
	v_mul_f32_e32 v60, v60, v206
	v_mul_f32_e32 v61, v61, v207
	v_mul_f32_e32 v62, v62, v208
	v_mul_f32_e32 v63, v63, v209
	v_mul_f32_e32 v64, v64, v210
	v_mul_f32_e32 v65, v65, v211
	v_mul_f32_e32 v66, v66, v212
	v_mul_f32_e32 v67, v67, v213
	v_mul_f32_e32 v36, v36, v198
	v_mul_f32_e32 v37, v37, v199
	v_mul_f32_e32 v38, v38, v200
	v_mul_f32_e32 v39, v39, v201
	v_mul_f32_e32 v40, v40, v202
	v_mul_f32_e32 v41, v41, v203
	v_mul_f32_e32 v42, v42, v204
	v_mul_f32_e32 v43, v43, v205
	v_mul_f32_e32 v44, v44, v206
	v_mul_f32_e32 v45, v45, v207
	v_mul_f32_e32 v46, v46, v208
	v_mul_f32_e32 v47, v47, v209
	v_mul_f32_e32 v48, v48, v210
	v_mul_f32_e32 v49, v49, v211
	v_mul_f32_e32 v50, v50, v212
	v_mul_f32_e32 v51, v51, v213
	ds_read_b128 v[198:201], v70 offset:128
	ds_read_b128 v[202:205], v70 offset:160
	ds_read_b128 v[206:209], v70 offset:192
	ds_read_b128 v[210:213], v70 offset:224
	ds_write2_b32 v34, v52, v53 offset1:130
	v_add_u32_e32 v214, 1040, v34
	ds_write2_b32 v214, v54, v55 offset1:130
	v_add_u32_e32 v214, 4160, v34
	ds_write2_b32 v214, v56, v57 offset1:130
	v_add_u32_e32 v214, 5200, v34
	ds_write2_b32 v214, v58, v59 offset1:130
	v_add_u32_e32 v214, 8320, v34
	ds_write2_b32 v214, v60, v61 offset1:130
	v_add_u32_e32 v214, 9360, v34
	ds_write2_b32 v214, v62, v63 offset1:130
	v_add_u32_e32 v214, 12480, v34
	ds_write2_b32 v214, v64, v65 offset1:130
	v_add_u32_e32 v214, 13520, v34
	ds_write2_b32 v214, v66, v67 offset1:130
	v_add_u32_e32 v214, 128, v34
	ds_write2_b32 v214, v36, v37 offset1:130
	v_add_u32_e32 v214, 1168, v34
	ds_write2_b32 v214, v38, v39 offset1:130
	v_add_u32_e32 v214, 4288, v34
	ds_write2_b32 v214, v40, v41 offset1:130
	v_add_u32_e32 v214, 5328, v34
	ds_write2_b32 v214, v42, v43 offset1:130
	v_add_u32_e32 v214, 8448, v34
	ds_write2_b32 v214, v44, v45 offset1:130
	v_add_u32_e32 v214, 9488, v34
	ds_write2_b32 v214, v46, v47 offset1:130
	v_add_u32_e32 v214, 12608, v34
	ds_write2_b32 v214, v48, v49 offset1:130
	v_add_u32_e32 v214, 13648, v34
	ds_write2_b32 v214, v50, v51 offset1:130
	s_waitcnt lgkmcnt(0)
	v_mul_f32_e32 v16, v16, v198
	v_mul_f32_e32 v17, v17, v199
	v_mul_f32_e32 v18, v18, v200
	v_mul_f32_e32 v19, v19, v201
	v_mul_f32_e32 v20, v20, v202
	v_mul_f32_e32 v21, v21, v203
	v_mul_f32_e32 v22, v22, v204
	v_mul_f32_e32 v23, v23, v205
	v_mul_f32_e32 v24, v24, v206
	v_mul_f32_e32 v25, v25, v207
	v_mul_f32_e32 v26, v26, v208
	v_mul_f32_e32 v27, v27, v209
	v_mul_f32_e32 v28, v28, v210
	v_mul_f32_e32 v29, v29, v211
	v_mul_f32_e32 v30, v30, v212
	v_mul_f32_e32 v31, v31, v213
	v_mul_f32_e32 v0, v0, v198
	v_mul_f32_e32 v1, v1, v199
	v_mul_f32_e32 v2, v2, v200
	v_mul_f32_e32 v3, v3, v201
	v_mul_f32_e32 v4, v4, v202
	v_mul_f32_e32 v5, v5, v203
	v_mul_f32_e32 v6, v6, v204
	v_mul_f32_e32 v7, v7, v205
	v_mul_f32_e32 v8, v8, v206
	v_mul_f32_e32 v9, v9, v207
	v_mul_f32_e32 v10, v10, v208
	v_mul_f32_e32 v11, v11, v209
	v_mul_f32_e32 v12, v12, v210
	v_mul_f32_e32 v13, v13, v211
	v_mul_f32_e32 v14, v14, v212
	v_mul_f32_e32 v15, v15, v213
	v_add_u32_e32 v214, 16640, v34
	ds_write2_b32 v214, v16, v17 offset1:130
	v_add_u32_e32 v214, 17680, v34
	ds_write2_b32 v214, v18, v19 offset1:130
	v_add_u32_e32 v214, 20800, v34
	ds_write2_b32 v214, v20, v21 offset1:130
	v_add_u32_e32 v214, 21840, v34
	ds_write2_b32 v214, v22, v23 offset1:130
	v_add_u32_e32 v214, 24960, v34
	ds_write2_b32 v214, v24, v25 offset1:130
	v_add_u32_e32 v214, 26000, v34
	ds_write2_b32 v214, v26, v27 offset1:130
	v_add_u32_e32 v214, 29120, v34
	ds_write2_b32 v214, v28, v29 offset1:130
	v_add_u32_e32 v214, 30160, v34
	ds_write2_b32 v214, v30, v31 offset1:130
	v_add_u32_e32 v214, 16768, v34
	ds_write2_b32 v214, v0, v1 offset1:130
	v_add_u32_e32 v214, 17808, v34
	ds_write2_b32 v214, v2, v3 offset1:130
	v_add_u32_e32 v214, 20928, v34
	ds_write2_b32 v214, v4, v5 offset1:130
	v_add_u32_e32 v214, 21968, v34
	ds_write2_b32 v214, v6, v7 offset1:130
	v_add_u32_e32 v214, 25088, v34
	ds_write2_b32 v214, v8, v9 offset1:130
	v_add_u32_e32 v214, 26128, v34
	ds_write2_b32 v214, v10, v11 offset1:130
	v_add_u32_e32 v214, 29248, v34
	ds_write2_b32 v214, v12, v13 offset1:130
	v_add_u32_e32 v214, 30288, v34
	ds_write2_b32 v214, v14, v15 offset1:130
	v_lshlrev_b32_e32 v16, 4, v68
	v_or_b32_e32 v8, s11, v16
	v_add_u32_e32 v12, 16, v8
	v_min3_i32 v14, s12, v12, v193
	v_cmp_lt_i32_e32 vcc, v8, v14
	s_waitcnt lgkmcnt(0)
	s_barrier
	s_and_saveexec_b64 s[16:17], vcc
	s_cbranch_execz .LBB0_57
	s_load_dwordx2 s[12:13], s[0:1], 0xe0
	s_movk_i32 s15, 0x208
	v_mul_lo_u32 v0, v8, s15
	s_ashr_i32 s15, s14, 31
	s_lshl_b64 s[18:19], s[14:15], 13
	s_ashr_i32 s15, s10, 31
	s_add_u32 s18, s18, s10
	v_lshlrev_b32_e32 v1, 2, v164
	s_addc_u32 s19, s19, s15
	v_ashrrev_i32_e32 v9, 31, v8
	v_add3_u32 v15, 0, v0, v1
	v_lshl_add_u64 v[0:1], s[18:19], 0, v[8:9]
	s_waitcnt lgkmcnt(0)
	v_mov_b64_e32 v[2:3], s[12:13]
	s_movk_i32 s10, 0x1600
	v_mad_u64_u32 v[2:3], s[12:13], v0, s10, v[2:3]
	v_mad_i32_i24 v3, v1, s10, v3
	v_lshl_add_u64 v[0:1], v[146:147], 1, v[2:3]
	s_mov_b64 s[12:13], 0xa180000
	v_lshl_add_u64 v[10:11], v[0:1], 0, s[12:13]
	ds_read2_b64 v[0:3], v15 offset1:32
	ds_read2_b64 v[4:7], v15 offset0:65 offset1:97
	v_and_b32_e32 v13, 2, v14
	v_cmp_ne_u32_e32 vcc, 0, v13
	s_and_saveexec_b64 s[18:19], vcc
	s_cbranch_execz .LBB0_84
	s_and_b32 s10, s7, 7
	s_add_i32 s9, s9, s10
	s_mul_i32 s10, s14, 0x42
	s_sub_i32 s9, s9, s10
	s_mulk_i32 s9, 0x7e
	s_sub_i32 s9, 0x2000, s9
	v_min3_i32 v8, v12, s9, v193
	v_bfe_u32 v8, v8, 1, 1
	v_mul_u32_u24_e32 v9, 0x410, v8
	v_add3_u32 v8, s11, v16, v13
	s_mov_b32 s9, 0
	s_mov_b64 s[14:15], 0
	s_waitcnt vmcnt(0)

; DI int tid() { int t = threadIdx.x; asm volatile("" : "+v"(t)); return t; }
; DI int crow(int r, int h) { return (r & 3) + 8 * (r >> 2) + 4 * h; }
; DI float* stage_tile(const f32x16 (&acc)[2][2], const float* rs, char* smem) {
;     const int tt = tid(), lane = tt & 63, w = __builtin_amdgcn_readfirstlane(tt >> 6), wm = w >> 1, wn = w & 1, l32 = lane & 31, h = lane >> 5;
;     float* stg = (float*)smem;
; #pragma unroll
;     for (int i = 0; i < 2; ++i)
; #pragma unroll
;         for (int j = 0; j < 2; ++j)
; #pragma unroll
;             for (int r = 0; r < 16; ++r) {
;                 const int row = wm * 64 + i * 32 + crow(r, h);
;                 stg[row * 132 + wn * 64 + j * 32 + l32] = rs ? acc[i][j][r] * rs[row] : acc[i][j][r];
;             }
;     __syncthreads();
;     return stg;
; DI void ph_qm(KP p, int l, char* smem) {
;     ...
;         const float rsp = rs_load(p, rt * 128);
;         gemm_tile<0, true>((const bf16_t*)(p->ws + OFF_XB), DM, rt * 128, 0, TOK, (const bf16_t*)(p->ws + OFF_WMQ) + ((size_t)l * DM + ct * 128) * DM, DM, DM, smem, acc);
;         rs_finish(rsp, rt * 128, smem);
;         const float* stg = stage_tile(acc, (const float*)(smem + RS_OFF), smem);
.LBB0_136:
	s_or_b64 exec, exec, s[18:19]
	v_mov_b32_e32 v32, v182
	s_waitcnt lgkmcnt(0)
	s_barrier
	s_nop 0
	s_waitcnt vmcnt(0)
	v_readfirstlane_b32 s7, v32
	v_and_b32_e32 v33, 31, v32
	s_ashr_i32 s8, s7, 1
	v_lshrrev_b32_e32 v32, 3, v32
	s_andn2_b32 s8, s8, 63
	v_and_b32_e32 v68, 4, v32
	v_and_or_b32 v32, s7, 64, v33
	v_or_b32_e32 v33, s8, v68
	s_add_i32 s7, 0, 0x12000
	v_lshl_add_u32 v69, v33, 2, s7
	v_mul_lo_u32 v33, v33, s82
	v_lshlrev_b32_e32 v32, 2, v32
	v_add3_u32 v34, 0, v33, v32
	ds_read_b128 v[70:73], v69
	ds_read_b128 v[74:77], v69 offset:32
	ds_read_b128 v[78:81], v69 offset:64
	ds_read_b128 v[82:85], v69 offset:96
	s_waitcnt lgkmcnt(0)
	v_mul_f32_e32 v36, v36, v70
	v_mul_f32_e32 v37, v37, v71
	v_mul_f32_e32 v38, v38, v72
	v_mul_f32_e32 v39, v39, v73
	v_mul_f32_e32 v40, v40, v74
	v_mul_f32_e32 v41, v41, v75
	v_mul_f32_e32 v42, v42, v76
	v_mul_f32_e32 v43, v43, v77
	v_mul_f32_e32 v44, v44, v78
	v_mul_f32_e32 v45, v45, v79
	v_mul_f32_e32 v46, v46, v80
	v_mul_f32_e32 v47, v47, v81
	v_mul_f32_e32 v48, v48, v82
	v_mul_f32_e32 v49, v49, v83
	v_mul_f32_e32 v50, v50, v84
	v_mul_f32_e32 v51, v51, v85
	v_mul_f32_e32 v52, v52, v70
	v_mul_f32_e32 v53, v53, v71
	v_mul_f32_e32 v54, v54, v72
	v_mul_f32_e32 v55, v55, v73
	v_mul_f32_e32 v56, v56, v74
	v_mul_f32_e32 v57, v57, v75
	v_mul_f32_e32 v58, v58, v76
	v_mul_f32_e32 v59, v59, v77
	v_mul_f32_e32 v60, v60, v78
	v_mul_f32_e32 v61, v61, v79
	v_mul_f32_e32 v62, v62, v80
	v_mul_f32_e32 v63, v63, v81
	v_mul_f32_e32 v64, v64, v82
	v_mul_f32_e32 v65, v65, v83
	v_mul_f32_e32 v66, v66, v84
	v_mul_f32_e32 v67, v67, v85
	ds_read_b128 v[70:73], v69 offset:128
	ds_read_b128 v[74:77], v69 offset:160
	ds_read_b128 v[78:81], v69 offset:192
	ds_read_b128 v[82:85], v69 offset:224
	ds_write2_b32 v34, v36, v37 offset1:132
	v_add_u32_e32 v86, 1056, v34
	ds_write2_b32 v86, v38, v39 offset1:132
	v_add_u32_e32 v86, 4224, v34
	ds_write2_b32 v86, v40, v41 offset1:132
	v_add_u32_e32 v86, 5280, v34
	ds_write2_b32 v86, v42, v43 offset1:132
	v_add_u32_e32 v86, 8448, v34
	ds_write2_b32 v86, v44, v45 offset1:132
	v_add_u32_e32 v86, 9504, v34
	ds_write2_b32 v86, v46, v47 offset1:132
	v_add_u32_e32 v86, 12672, v34
	ds_write2_b32 v86, v48, v49 offset1:132
	v_add_u32_e32 v86, 13728, v34
	ds_write2_b32 v86, v50, v51 offset1:132
	v_add_u32_e32 v86, 128, v34
	ds_write2_b32 v86, v52, v53 offset1:132
	v_add_u32_e32 v86, 1184, v34
	ds_write2_b32 v86, v54, v55 offset1:132
	v_add_u32_e32 v86, 4352, v34
	ds_write2_b32 v86, v56, v57 offset1:132
	v_add_u32_e32 v86, 5408, v34
	ds_write2_b32 v86, v58, v59 offset1:132
	v_add_u32_e32 v86, 8576, v34
	ds_write2_b32 v86, v60, v61 offset1:132
	v_add_u32_e32 v86, 9632, v34
	ds_write2_b32 v86, v62, v63 offset1:132
	v_add_u32_e32 v86, 12800, v34
	ds_write2_b32 v86, v64, v65 offset1:132
	v_add_u32_e32 v86, 13856, v34
	ds_write2_b32 v86, v66, v67 offset1:132
	s_waitcnt lgkmcnt(0)
	v_mul_f32_e32 v16, v16, v70
	v_mul_f32_e32 v17, v17, v71
	v_mul_f32_e32 v18, v18, v72
	v_mul_f32_e32 v19, v19, v73
	v_mul_f32_e32 v20, v20, v74
	v_mul_f32_e32 v21, v21, v75
	v_mul_f32_e32 v22, v22, v76
	v_mul_f32_e32 v23, v23, v77
	v_mul_f32_e32 v24, v24, v78
	v_mul_f32_e32 v25, v25, v79
	v_mul_f32_e32 v26, v26, v80
	v_mul_f32_e32 v27, v27, v81
	v_mul_f32_e32 v28, v28, v82
	v_mul_f32_e32 v29, v29, v83
	v_mul_f32_e32 v30, v30, v84
	v_mul_f32_e32 v31, v31, v85
	v_mul_f32_e32 v0, v0, v70
	v_mul_f32_e32 v1, v1, v71
	v_mul_f32_e32 v2, v2, v72
	v_mul_f32_e32 v3, v3, v73
	v_mul_f32_e32 v4, v4, v74
	v_mul_f32_e32 v5, v5, v75
	v_mul_f32_e32 v6, v6, v76
	v_mul_f32_e32 v7, v7, v77
	v_mul_f32_e32 v8, v8, v78
	v_mul_f32_e32 v9, v9, v79
	v_mul_f32_e32 v10, v10, v80
	v_mul_f32_e32 v11, v11, v81
	v_mul_f32_e32 v12, v12, v82
	v_mul_f32_e32 v13, v13, v83
	v_mul_f32_e32 v14, v14, v84
	v_mul_f32_e32 v15, v15, v85
	v_add_u32_e32 v86, 16896, v34
	ds_write2_b32 v86, v16, v17 offset1:132
	v_add_u32_e32 v86, 17952, v34
	ds_write2_b32 v86, v18, v19 offset1:132
	v_add_u32_e32 v86, 21120, v34
	ds_write2_b32 v86, v20, v21 offset1:132
	v_add_u32_e32 v86, 22176, v34
	ds_write2_b32 v86, v22, v23 offset1:132
	v_add_u32_e32 v86, 25344, v34
	ds_write2_b32 v86, v24, v25 offset1:132
	v_add_u32_e32 v86, 26400, v34
	ds_write2_b32 v86, v26, v27 offset1:132
	v_add_u32_e32 v86, 29568, v34
	ds_write2_b32 v86, v28, v29 offset1:132
	v_add_u32_e32 v86, 30624, v34
	ds_write2_b32 v86, v30, v31 offset1:132
	v_add_u32_e32 v86, 17024, v34
	ds_write2_b32 v86, v0, v1 offset1:132
	v_add_u32_e32 v86, 18080, v34
	ds_write2_b32 v86, v2, v3 offset1:132
	v_add_u32_e32 v86, 21248, v34
	ds_write2_b32 v86, v4, v5 offset1:132
	v_add_u32_e32 v86, 22304, v34
	ds_write2_b32 v86, v6, v7 offset1:132
	v_add_u32_e32 v86, 25472, v34
	ds_write2_b32 v86, v8, v9 offset1:132
	v_add_u32_e32 v86, 26528, v34
	ds_write2_b32 v86, v10, v11 offset1:132
	v_add_u32_e32 v86, 29696, v34
	ds_write2_b32 v86, v12, v13 offset1:132
	v_add_u32_e32 v86, 30752, v34
	ds_write2_b32 v86, v14, v15 offset1:132
	s_add_u32 s14, s14, 0xa180000
	s_addc_u32 s15, s15, 0
	s_lshl_b64 s[16:17], s[16:17], 1
	v_mov_b32_e32 v0, v182
	s_waitcnt lgkmcnt(0)
	s_barrier
; DI int tid() { int t = threadIdx.x; asm volatile("" : "+v"(t)); return t; }
; DI void st_nt16(void* p, const uint4& v) { u32x4 t = {v.x, v.y, v.z, v.w}; __builtin_nontemporal_store(t, (u32x4*)p); }
; DI uint4 pack8(const float4& a, const float4& b) { uint4 o; o.x = pack2(a.x, a.y); o.y = pack2(a.z, a.w); o.z = pack2(b.x, b.y); o.w = pack2(b.z, b.w); return o; }
; DI void ph_qm(KP p, int l, char* smem) {
;     ...
;         const int tt = tid(), c8 = tt & 15;
;         const float qs = 0.0625f * LOG2E;
; #pragma unroll
;         for (int i = 0; i < 8; ++i) {
;             const int row = (tt >> 4) + 16 * i;
;             float4 lo = *(const float4*)(stg + row * 132 + c8 * 8), hi = *(const float4*)(stg + row * 132 + c8 * 8 + 4);
;             lo.x *= qs; lo.y *= qs; lo.z *= qs; lo.w *= qs; hi.x *= qs; hi.y *= qs; hi.z *= qs; hi.w *= qs;
;             st_nt16((bf16_t*)(p->ws + OFF_QM) + (size_t)(rt * 128 + row) * DM + ct * 128 + c8 * 8, pack8(lo, hi));
;         }
	s_nop 0
	v_ashrrev_i32_e32 v8, 4, v0
	v_lshlrev_b32_e32 v0, 3, v0
	v_and_b32_e32 v11, 0x78, v0
	v_lshlrev_b32_e32 v0, 2, v11
	v_mul_lo_u32 v1, v8, s82
	v_add3_u32 v10, 0, v0, v1
	ds_read_b128 v[0:3], v10
	ds_read_b128 v[4:7], v10 offset:16
	v_add_u32_e32 v8, s6, v8
	v_ashrrev_i32_e32 v9, 31, v8
	v_lshlrev_b64 v[12:13], 11, v[8:9]
	v_lshl_add_u64 v[12:13], s[14:15], 0, v[12:13]
	s_waitcnt lgkmcnt(1)
	v_pk_mul_f32 v[0:1], v[0:1], s[50:51] op_sel_hi:[1,0]
	v_pk_mul_f32 v[2:3], v[2:3], s[50:51] op_sel_hi:[1,0]
	s_waitcnt lgkmcnt(0)
	v_pk_mul_f32 v[4:5], v[4:5], s[50:51] op_sel_hi:[1,0]
	v_pk_mul_f32 v[6:7], v[6:7], s[50:51] op_sel_hi:[1,0]
	v_lshl_add_u64 v[12:13], v[12:13], 0, s[16:17]
	v_lshlrev_b32_e32 v34, 1, v11
	v_lshl_add_u64 v[12:13], v[12:13], 0, v[34:35]
	v_cvt_pk_bf16_f32 v0, v0, v1
	v_cvt_pk_bf16_f32 v1, v2, v3
	v_cvt_pk_bf16_f32 v2, v4, v5
	v_cvt_pk_bf16_f32 v3, v6, v7
	global_store_dwordx4 v[12:13], v[0:3], off nt
	ds_read_b128 v[0:3], v10 offset:8448
	ds_read_b128 v[4:7], v10 offset:8464
	v_add_u32_e32 v12, 16, v8
	v_ashrrev_i32_e32 v13, 31, v12
	v_lshlrev_b64 v[12:13], 11, v[12:13]
	v_lshl_add_u64 v[12:13], s[14:15], 0, v[12:13]
	s_waitcnt lgkmcnt(1)
	v_pk_mul_f32 v[0:1], v[0:1], s[50:51] op_sel_hi:[1,0]
	v_pk_mul_f32 v[2:3], v[2:3], s[50:51] op_sel_hi:[1,0]
	s_waitcnt lgkmcnt(0)
	v_pk_mul_f32 v[4:5], v[4:5], s[50:51] op_sel_hi:[1,0]
	v_pk_mul_f32 v[6:7], v[6:7], s[50:51] op_sel_hi:[1,0]
	v_lshl_add_u64 v[12:13], v[12:13], 0, s[16:17]
	v_lshl_add_u64 v[12:13], v[12:13], 0, v[34:35]
	v_cvt_pk_bf16_f32 v0, v0, v1
	v_cvt_pk_bf16_f32 v1, v2, v3
	v_cvt_pk_bf16_f32 v2, v4, v5
	v_cvt_pk_bf16_f32 v3, v6, v7
	global_store_dwordx4 v[12:13], v[0:3], off nt
	ds_read_b128 v[0:3], v10 offset:16896
	ds_read_b128 v[4:7], v10 offset:16912
	v_add_u32_e32 v12, 32, v8
	v_ashrrev_i32_e32 v13, 31, v12
	v_lshlrev_b64 v[12:13], 11, v[12:13]
	v_lshl_add_u64 v[12:13], s[14:15], 0, v[12:13]
	s_waitcnt lgkmcnt(1)
	v_pk_mul_f32 v[0:1], v[0:1], s[50:51] op_sel_hi:[1,0]
	v_pk_mul_f32 v[2:3], v[2:3], s[50:51] op_sel_hi:[1,0]
	s_waitcnt lgkmcnt(0)
	v_pk_mul_f32 v[4:5], v[4:5], s[50:51] op_sel_hi:[1,0]
	v_pk_mul_f32 v[6:7], v[6:7], s[50:51] op_sel_hi:[1,0]
	v_lshl_add_u64 v[12:13], v[12:13], 0, s[16:17]
	v_lshl_add_u64 v[12:13], v[12:13], 0, v[34:35]
	v_cvt_pk_bf16_f32 v0, v0, v1
	v_cvt_pk_bf16_f32 v1, v2, v3
	v_cvt_pk_bf16_f32 v2, v4, v5
	v_cvt_pk_bf16_f32 v3, v6, v7
	global_store_dwordx4 v[12:13], v[0:3], off nt
	ds_read_b128 v[0:3], v10 offset:25344
	ds_read_b128 v[4:7], v10 offset:25360
	v_add_u32_e32 v12, 48, v8
	v_ashrrev_i32_e32 v13, 31, v12
	v_lshlrev_b64 v[12:13], 11, v[12:13]
	v_lshl_add_u64 v[12:13], s[14:15], 0, v[12:13]
	s_waitcnt lgkmcnt(1)
	v_pk_mul_f32 v[0:1], v[0:1], s[50:51] op_sel_hi:[1,0]
	v_pk_mul_f32 v[2:3], v[2:3], s[50:51] op_sel_hi:[1,0]
	s_waitcnt lgkmcnt(0)
	v_pk_mul_f32 v[4:5], v[4:5], s[50:51] op_sel_hi:[1,0]
	v_pk_mul_f32 v[6:7], v[6:7], s[50:51] op_sel_hi:[1,0]
	v_lshl_add_u64 v[12:13], v[12:13], 0, s[16:17]
	v_lshl_add_u64 v[12:13], v[12:13], 0, v[34:35]
	v_cvt_pk_bf16_f32 v0, v0, v1
	v_cvt_pk_bf16_f32 v1, v2, v3
	v_cvt_pk_bf16_f32 v2, v4, v5
	v_cvt_pk_bf16_f32 v3, v6, v7
	global_store_dwordx4 v[12:13], v[0:3], off nt
	ds_read_b128 v[0:3], v10 offset:33792
	ds_read_b128 v[4:7], v10 offset:33808
	v_add_u32_e32 v12, 64, v8
	v_ashrrev_i32_e32 v13, 31, v12
	v_lshlrev_b64 v[12:13], 11, v[12:13]
	v_lshl_add_u64 v[12:13], s[14:15], 0, v[12:13]
	s_waitcnt lgkmcnt(1)
	v_pk_mul_f32 v[0:1], v[0:1], s[50:51] op_sel_hi:[1,0]
	v_pk_mul_f32 v[2:3], v[2:3], s[50:51] op_sel_hi:[1,0]
	s_waitcnt lgkmcnt(0)
	v_pk_mul_f32 v[4:5], v[4:5], s[50:51] op_sel_hi:[1,0]
	v_pk_mul_f32 v[6:7], v[6:7], s[50:51] op_sel_hi:[1,0]
	v_lshl_add_u64 v[12:13], v[12:13], 0, s[16:17]
	v_lshl_add_u64 v[12:13], v[12:13], 0, v[34:35]
	v_cvt_pk_bf16_f32 v0, v0, v1
	v_cvt_pk_bf16_f32 v1, v2, v3
	v_cvt_pk_bf16_f32 v2, v4, v5
	v_cvt_pk_bf16_f32 v3, v6, v7
	global_store_dwordx4 v[12:13], v[0:3], off nt
	ds_read_b128 v[0:3], v10 offset:42240
	ds_read_b128 v[4:7], v10 offset:42256
	v_add_u32_e32 v12, 0x50, v8
	v_ashrrev_i32_e32 v13, 31, v12
	v_lshlrev_b64 v[12:13], 11, v[12:13]
	v_lshl_add_u64 v[12:13], s[14:15], 0, v[12:13]
	s_waitcnt lgkmcnt(1)
	v_pk_mul_f32 v[0:1], v[0:1], s[50:51] op_sel_hi:[1,0]
	v_pk_mul_f32 v[2:3], v[2:3], s[50:51] op_sel_hi:[1,0]
	s_waitcnt lgkmcnt(0)
	v_pk_mul_f32 v[4:5], v[4:5], s[50:51] op_sel_hi:[1,0]
	v_pk_mul_f32 v[6:7], v[6:7], s[50:51] op_sel_hi:[1,0]
	v_lshl_add_u64 v[12:13], v[12:13], 0, s[16:17]
	v_lshl_add_u64 v[12:13], v[12:13], 0, v[34:35]
	v_cvt_pk_bf16_f32 v0, v0, v1
	v_cvt_pk_bf16_f32 v1, v2, v3
	v_cvt_pk_bf16_f32 v2, v4, v5
	v_cvt_pk_bf16_f32 v3, v6, v7
	global_store_dwordx4 v[12:13], v[0:3], off nt
	ds_read_b128 v[4:7], v10 offset:50688
	ds_read_b128 v[0:3], v10 offset:50704
	s_waitcnt lgkmcnt(1)
	v_pk_mul_f32 v[4:5], v[4:5], s[50:51] op_sel_hi:[1,0]
	s_waitcnt lgkmcnt(0)
	v_pk_mul_f32 v[12:13], v[0:1], s[50:51] op_sel_hi:[1,0]
	v_add_u32_e32 v0, 0x60, v8
	v_ashrrev_i32_e32 v1, 31, v0
	v_lshlrev_b64 v[0:1], 11, v[0:1]
	v_lshl_add_u64 v[0:1], s[14:15], 0, v[0:1]
	v_pk_mul_f32 v[6:7], v[6:7], s[50:51] op_sel_hi:[1,0]
	v_pk_mul_f32 v[14:15], v[2:3], s[50:51] op_sel_hi:[1,0]
	v_lshl_add_u64 v[0:1], v[0:1], 0, s[16:17]
	v_lshl_add_u64 v[16:17], v[0:1], 0, v[34:35]
	v_cvt_pk_bf16_f32 v0, v4, v5
	v_cvt_pk_bf16_f32 v1, v6, v7
	v_cvt_pk_bf16_f32 v2, v12, v13
	v_cvt_pk_bf16_f32 v3, v14, v15
	global_store_dwordx4 v[16:17], v[0:3], off nt
	ds_read_b128 v[0:3], v10 offset:59136
	ds_read_b128 v[4:7], v10 offset:59152
	v_add_u32_e32 v8, 0x70, v8
	v_ashrrev_i32_e32 v9, 31, v8
	v_lshlrev_b64 v[8:9], 11, v[8:9]
	v_lshl_add_u64 v[8:9], s[14:15], 0, v[8:9]
	s_waitcnt lgkmcnt(1)
	v_pk_mul_f32 v[0:1], v[0:1], s[50:51] op_sel_hi:[1,0]
	v_pk_mul_f32 v[2:3], v[2:3], s[50:51] op_sel_hi:[1,0]
	s_waitcnt lgkmcnt(0)
	v_pk_mul_f32 v[4:5], v[4:5], s[50:51] op_sel_hi:[1,0]
	v_pk_mul_f32 v[6:7], v[6:7], s[50:51] op_sel_hi:[1,0]
	v_lshl_add_u64 v[8:9], v[8:9], 0, s[16:17]
	v_lshl_add_u64 v[8:9], v[8:9], 0, v[34:35]
	v_cvt_pk_bf16_f32 v0, v0, v1
	v_cvt_pk_bf16_f32 v1, v2, v3
	v_cvt_pk_bf16_f32 v2, v4, v5
	v_cvt_pk_bf16_f32 v3, v6, v7
	global_store_dwordx4 v[8:9], v[0:3], off nt

; DI int tid() { int t = threadIdx.x; asm volatile("" : "+v"(t)); return t; }
; DI int crow(int r, int h) { return (r & 3) + 8 * (r >> 2) + 4 * h; }
; DI float* stage_tile(const f32x16 (&acc)[2][2], const float* rs, char* smem) {
;     const int tt = tid(), lane = tt & 63, w = __builtin_amdgcn_readfirstlane(tt >> 6), wm = w >> 1, wn = w & 1, l32 = lane & 31, h = lane >> 5;
;     float* stg = (float*)smem;
; #pragma unroll
;     for (int i = 0; i < 2; ++i)
; #pragma unroll
;         for (int j = 0; j < 2; ++j)
; #pragma unroll
;             for (int r = 0; r < 16; ++r) {
;                 const int row = wm * 64 + i * 32 + crow(r, h);
;                 stg[row * 132 + wn * 64 + j * 32 + l32] = rs ? acc[i][j][r] * rs[row] : acc[i][j][r];
;             }
;     __syncthreads();
;     return stg;
; }
; DI void ph_qkv(KP p, int l, char* smem) {
;     ...
;             const int c2 = ct - 6;
;             gemm_tile<1>((const bf16_t*)(p->ws + OFF_HKV), KVL, rt * 128, 0, TOK, (const bf16_t*)(p->ws + OFF_WUKV) + ((size_t)l * 1024 + c2 * 128) * KVL, KVL, KVL, smem, acc);
;             const float* stg = stage_tile(acc, (const float*)(smem + RS_OFF), smem);
.LBB0_202:
	s_or_b64 exec, exec, s[16:17]
	v_mov_b32_e32 v32, v182
	s_waitcnt lgkmcnt(0)
	s_barrier
	v_readfirstlane_b32 s11, v32
	v_and_b32_e32 v33, 31, v32
	s_ashr_i32 s12, s11, 1
	v_lshrrev_b32_e32 v32, 3, v32
	s_andn2_b32 s12, s12, 63
	v_and_b32_e32 v68, 4, v32
	v_and_or_b32 v32, s11, 64, v33
	v_or_b32_e32 v33, s12, v68
	s_add_i32 s11, 0, 0x12000
	v_lshl_add_u32 v69, v33, 2, s11
	v_mul_lo_u32 v33, v33, s82
	v_lshlrev_b32_e32 v32, 2, v32
	v_add3_u32 v34, 0, v33, v32
	ds_read_b128 v[70:73], v69
	ds_read_b128 v[74:77], v69 offset:32
	ds_read_b128 v[78:81], v69 offset:64
	ds_read_b128 v[82:85], v69 offset:96
	s_waitcnt lgkmcnt(0)
	v_mul_f32_e32 v52, v52, v70
	v_mul_f32_e32 v53, v53, v71
	v_mul_f32_e32 v54, v54, v72
	v_mul_f32_e32 v55, v55, v73
	v_mul_f32_e32 v56, v56, v74
	v_mul_f32_e32 v57, v57, v75
	v_mul_f32_e32 v58, v58, v76
	v_mul_f32_e32 v59, v59, v77
	v_mul_f32_e32 v60, v60, v78
	v_mul_f32_e32 v61, v61, v79
	v_mul_f32_e32 v62, v62, v80
	v_mul_f32_e32 v63, v63, v81
	v_mul_f32_e32 v64, v64, v82
	v_mul_f32_e32 v65, v65, v83
	v_mul_f32_e32 v66, v66, v84
	v_mul_f32_e32 v67, v67, v85
	v_mul_f32_e32 v36, v36, v70
	v_mul_f32_e32 v37, v37, v71
	v_mul_f32_e32 v38, v38, v72
	v_mul_f32_e32 v39, v39, v73
	v_mul_f32_e32 v40, v40, v74
	v_mul_f32_e32 v41, v41, v75
	v_mul_f32_e32 v42, v42, v76
	v_mul_f32_e32 v43, v43, v77
	v_mul_f32_e32 v44, v44, v78
	v_mul_f32_e32 v45, v45, v79
	v_mul_f32_e32 v46, v46, v80
	v_mul_f32_e32 v47, v47, v81
	v_mul_f32_e32 v48, v48, v82
	v_mul_f32_e32 v49, v49, v83
	v_mul_f32_e32 v50, v50, v84
	v_mul_f32_e32 v51, v51, v85
	ds_read_b128 v[70:73], v69 offset:128
	ds_read_b128 v[74:77], v69 offset:160
	ds_read_b128 v[78:81], v69 offset:192
	ds_read_b128 v[82:85], v69 offset:224
	ds_write2_b32 v34, v52, v53 offset1:132
	v_add_u32_e32 v86, 1056, v34
	ds_write2_b32 v86, v54, v55 offset1:132
	v_add_u32_e32 v86, 4224, v34
	ds_write2_b32 v86, v56, v57 offset1:132
	v_add_u32_e32 v86, 5280, v34
	ds_write2_b32 v86, v58, v59 offset1:132
	v_add_u32_e32 v86, 8448, v34
	ds_write2_b32 v86, v60, v61 offset1:132
	v_add_u32_e32 v86, 9504, v34
	ds_write2_b32 v86, v62, v63 offset1:132
	v_add_u32_e32 v86, 12672, v34
	ds_write2_b32 v86, v64, v65 offset1:132
	v_add_u32_e32 v86, 13728, v34
	ds_write2_b32 v86, v66, v67 offset1:132
	v_add_u32_e32 v86, 128, v34
	ds_write2_b32 v86, v36, v37 offset1:132
	v_add_u32_e32 v86, 1184, v34
	ds_write2_b32 v86, v38, v39 offset1:132
	v_add_u32_e32 v86, 4352, v34
	ds_write2_b32 v86, v40, v41 offset1:132
	v_add_u32_e32 v86, 5408, v34
	ds_write2_b32 v86, v42, v43 offset1:132
	v_add_u32_e32 v86, 8576, v34
	ds_write2_b32 v86, v44, v45 offset1:132
	v_add_u32_e32 v86, 9632, v34
	ds_write2_b32 v86, v46, v47 offset1:132
	v_add_u32_e32 v86, 12800, v34
	ds_write2_b32 v86, v48, v49 offset1:132
	v_add_u32_e32 v86, 13856, v34
	ds_write2_b32 v86, v50, v51 offset1:132
	s_waitcnt lgkmcnt(0)
	v_mul_f32_e32 v16, v16, v70
	v_mul_f32_e32 v17, v17, v71
	v_mul_f32_e32 v18, v18, v72
	v_mul_f32_e32 v19, v19, v73
	v_mul_f32_e32 v20, v20, v74
	v_mul_f32_e32 v21, v21, v75
	v_mul_f32_e32 v22, v22, v76
	v_mul_f32_e32 v23, v23, v77
	v_mul_f32_e32 v24, v24, v78
	v_mul_f32_e32 v25, v25, v79
	v_mul_f32_e32 v26, v26, v80
	v_mul_f32_e32 v27, v27, v81
	v_mul_f32_e32 v28, v28, v82
	v_mul_f32_e32 v29, v29, v83
	v_mul_f32_e32 v30, v30, v84
	v_mul_f32_e32 v31, v31, v85
	v_mul_f32_e32 v0, v0, v70
	v_mul_f32_e32 v1, v1, v71
	v_mul_f32_e32 v2, v2, v72
	v_mul_f32_e32 v3, v3, v73
	v_mul_f32_e32 v4, v4, v74
	v_mul_f32_e32 v5, v5, v75
	v_mul_f32_e32 v6, v6, v76
	v_mul_f32_e32 v7, v7, v77
	v_mul_f32_e32 v8, v8, v78
	v_mul_f32_e32 v9, v9, v79
	v_mul_f32_e32 v10, v10, v80
	v_mul_f32_e32 v11, v11, v81
	v_mul_f32_e32 v12, v12, v82
	v_mul_f32_e32 v13, v13, v83
	v_mul_f32_e32 v14, v14, v84
	v_mul_f32_e32 v15, v15, v85
	v_add_u32_e32 v86, 16896, v34
	ds_write2_b32 v86, v16, v17 offset1:132
	v_add_u32_e32 v86, 17952, v34
	ds_write2_b32 v86, v18, v19 offset1:132
	v_add_u32_e32 v86, 21120, v34
	ds_write2_b32 v86, v20, v21 offset1:132
	v_add_u32_e32 v86, 22176, v34
	ds_write2_b32 v86, v22, v23 offset1:132
	v_add_u32_e32 v86, 25344, v34
	ds_write2_b32 v86, v24, v25 offset1:132
	v_add_u32_e32 v86, 26400, v34
	ds_write2_b32 v86, v26, v27 offset1:132
	v_add_u32_e32 v86, 29568, v34
	ds_write2_b32 v86, v28, v29 offset1:132
	v_add_u32_e32 v86, 30624, v34
	ds_write2_b32 v86, v30, v31 offset1:132
	v_add_u32_e32 v86, 17024, v34
	ds_write2_b32 v86, v0, v1 offset1:132
	v_add_u32_e32 v86, 18080, v34
	ds_write2_b32 v86, v2, v3 offset1:132
	v_add_u32_e32 v86, 21248, v34
	ds_write2_b32 v86, v4, v5 offset1:132
	v_add_u32_e32 v86, 22304, v34
	ds_write2_b32 v86, v6, v7 offset1:132
	v_add_u32_e32 v86, 25472, v34
	ds_write2_b32 v86, v8, v9 offset1:132
	v_add_u32_e32 v86, 26528, v34
	ds_write2_b32 v86, v10, v11 offset1:132
	v_add_u32_e32 v86, 29696, v34
	ds_write2_b32 v86, v12, v13 offset1:132
	v_add_u32_e32 v86, 30752, v34
	ds_write2_b32 v86, v14, v15 offset1:132
	s_and_b32 s8, s8, -8
	s_add_i32 s8, s9, s8
	s_ashr_i32 s9, s8, 31
	s_and_b32 s16, s10, 0x1f80
	s_lshl_b64 s[10:11], s[8:9], 13
	s_or_b32 s10, s10, s16
	s_add_u32 s12, s14, 0x10180000
	s_addc_u32 s13, s15, 0
	s_lshl_b64 s[8:9], s[8:9], 20
	s_add_u32 s8, s14, s8
	s_addc_u32 s9, s15, s9
	s_lshl_b32 s56, s16, 7
	s_mov_b64 s[14:15], 0
	v_mov_b32_e32 v16, v182
	v_mov_b64_e32 v[12:13], s[12:13]
	s_waitcnt lgkmcnt(0)
	s_barrier
; DI unsigned pack2(float a, float b) { f32v2_t v = {a, b}; return __builtin_bit_cast(unsigned, __builtin_convertvector(v, bf16v2_t)); }
; DI int tid() { int t = threadIdx.x; asm volatile("" : "+v"(t)); return t; }
; DI void st_nt16(void* p, const uint4& v) { u32x4 t = {v.x, v.y, v.z, v.w}; __builtin_nontemporal_store(t, (u32x4*)p); }
; DI uint4 pack8(const float4& a, const float4& b) { uint4 o; o.x = pack2(a.x, a.y); o.y = pack2(a.z, a.w); o.z = pack2(b.x, b.y); o.w = pack2(b.z, b.w); return o; }
; DI void ph_qkv(KP p, int l, char* smem) {
;     ...
;             const int tt = tid(), tok0 = rt * 128, b = tok0 >> 13, s0 = tok0 & 8191;
;             {
;                 const int c8 = tt & 7;
; #pragma unroll
;                 for (int i = 0; i < 4; ++i) {
;                     const int row = (tt >> 3) + 32 * i;
;                     const float4 lo = *(const float4*)(stg + row * 132 + c8 * 8), hi = *(const float4*)(stg + row * 132 + c8 * 8 + 4);
;                     st_nt16((bf16_t*)(p->ws + OFF_K) + (((size_t)(b * 8 + c2)) * SEQ + s0 + row) * 96 + c8 * 8, pack8(lo, hi));
;                 }
;             }
;             {
;                 const int tc = tt & 15;
; #pragma unroll
;                 for (int i = 0; i < 4; ++i) {
;                     const int d = (tt >> 4) + 16 * i;
;                     const float* sp = stg + (tc * 8) * 132 + 64 + d;
;                     uint4 ov;
;                     ov.x = pack2(sp[0], sp[132]); ov.y = pack2(sp[2 * 132], sp[3 * 132]); ov.z = pack2(sp[4 * 132], sp[5 * 132]); ov.w = pack2(sp[6 * 132], sp[7 * 132]);
;                     st_nt16((bf16_t*)(p->ws + OFF_VT) + (((size_t)(b * 8 + c2)) * 64 + d) * SEQ + s0 + tc * 8, ov);
;                 }
;             }
	s_nop 0
	v_lshlrev_b32_e32 v17, 3, v16
	v_ashrrev_i32_e32 v8, 3, v16
	v_and_b32_e32 v18, 56, v17
	v_lshlrev_b32_e32 v0, 2, v18
	v_mul_lo_u32 v1, v8, s82
	v_add3_u32 v19, 0, v0, v1
	ds_read_b128 v[0:3], v19
	ds_read_b128 v[4:7], v19 offset:16
	v_ashrrev_i32_e32 v9, 31, v8
	v_lshl_add_u64 v[10:11], s[10:11], 0, v[8:9]
	v_mad_u64_u32 v[14:15], s[12:13], v10, s86, v[12:13]
	v_mad_i32_i24 v15, v11, s86, v15
	v_lshlrev_b32_e32 v34, 1, v18
	v_lshl_add_u64 v[10:11], v[14:15], 0, v[34:35]
	s_waitcnt lgkmcnt(1)
	v_cvt_pk_bf16_f32 v0, v0, v1
	v_cvt_pk_bf16_f32 v1, v2, v3
	s_waitcnt lgkmcnt(0)
	v_cvt_pk_bf16_f32 v2, v4, v5
	v_cvt_pk_bf16_f32 v3, v6, v7
	global_store_dwordx4 v[10:11], v[0:3], off nt
	v_add_u32_e32 v10, 32, v8
	ds_read_b128 v[0:3], v19 offset:16896
	ds_read_b128 v[4:7], v19 offset:16912
	v_ashrrev_i32_e32 v11, 31, v10
	v_lshl_add_u64 v[10:11], s[10:11], 0, v[10:11]
	v_mad_u64_u32 v[14:15], s[12:13], v10, s86, v[12:13]
	v_mad_i32_i24 v15, v11, s86, v15
	v_lshl_add_u64 v[10:11], v[14:15], 0, v[34:35]
	s_waitcnt lgkmcnt(1)
	v_cvt_pk_bf16_f32 v0, v0, v1
	v_cvt_pk_bf16_f32 v1, v2, v3
	s_waitcnt lgkmcnt(0)
	v_cvt_pk_bf16_f32 v2, v4, v5
	v_cvt_pk_bf16_f32 v3, v6, v7
	global_store_dwordx4 v[10:11], v[0:3], off nt
	v_add_u32_e32 v10, 64, v8
	ds_read_b128 v[0:3], v19 offset:33792
	ds_read_b128 v[4:7], v19 offset:33808
	v_ashrrev_i32_e32 v11, 31, v10
	v_lshl_add_u64 v[10:11], s[10:11], 0, v[10:11]
	v_mad_u64_u32 v[14:15], s[12:13], v10, s86, v[12:13]
	v_mad_i32_i24 v15, v11, s86, v15
	v_lshl_add_u64 v[10:11], v[14:15], 0, v[34:35]
	s_waitcnt lgkmcnt(1)
	v_cvt_pk_bf16_f32 v0, v0, v1
	v_cvt_pk_bf16_f32 v1, v2, v3
	s_waitcnt lgkmcnt(0)
	v_cvt_pk_bf16_f32 v2, v4, v5
	v_cvt_pk_bf16_f32 v3, v6, v7
	global_store_dwordx4 v[10:11], v[0:3], off nt
	v_add_u32_e32 v8, 0x60, v8
	ds_read_b128 v[0:3], v19 offset:50688
	ds_read_b128 v[4:7], v19 offset:50704
	v_ashrrev_i32_e32 v9, 31, v8
	v_lshl_add_u64 v[8:9], s[10:11], 0, v[8:9]
	v_mad_u64_u32 v[10:11], s[10:11], v8, s86, v[12:13]
	v_mad_i32_i24 v11, v9, s86, v11
	v_lshl_add_u64 v[8:9], v[10:11], 0, v[34:35]
	s_waitcnt lgkmcnt(1)
	v_cvt_pk_bf16_f32 v0, v0, v1
	v_cvt_pk_bf16_f32 v1, v2, v3
	s_waitcnt lgkmcnt(0)
	v_cvt_pk_bf16_f32 v2, v4, v5
	v_cvt_pk_bf16_f32 v3, v6, v7
	v_ashrrev_i32_e32 v4, 4, v16
	v_and_b32_e32 v24, 0x78, v17
	global_store_dwordx4 v[8:9], v[0:3], off nt
	v_ashrrev_i32_e32 v5, 31, v4
	v_lshlrev_b32_e32 v34, 1, v24
	v_and_b32_e32 v0, 0x80, v34
	v_and_b32_e32 v34, 0x70, v34
	v_lshl_or_b32 v34, v0, 6, v34
	v_mul_u32_u24_e32 v0, 0x210, v24
	v_lshlrev_b32_e32 v1, 2, v4
	v_add3_u32 v22, 0, v0, v1
	ds_read2_b32 v[6:7], v22 offset0:64 offset1:80
	ds_read2_b32 v[8:9], v22 offset0:196 offset1:212
	v_add_u32_e32 v23, 0x400, v22
	v_lshlrev_b64 v[4:5], 7, v[4:5]
	ds_read2_b32 v[10:11], v23 offset0:72 offset1:88
	ds_read2_b32 v[12:13], v23 offset0:204 offset1:220
	v_lshl_add_u64 v[4:5], s[8:9], 0, v[4:5]
	s_waitcnt lgkmcnt(2)
	v_cvt_pk_bf16_f32 v0, v6, v8
	v_add_u32_e32 v8, 0x800, v22
	v_add_u32_e32 v6, 0xc00, v22
	ds_read2_b32 v[14:15], v8 offset0:80 offset1:96
	ds_read2_b32 v[16:17], v8 offset0:212 offset1:228
	ds_read2_b32 v[18:19], v6 offset0:88 offset1:104
	ds_read2_b32 v[20:21], v6 offset0:220 offset1:236
	v_lshl_add_u64 v[4:5], v[4:5], 0, s[56:57]
	v_lshl_add_u64 v[4:5], v[4:5], 0, v[34:35]
	s_mov_b32 s8, 0x16180000
	v_add_co_u32_e32 v24, vcc, s8, v4
	s_mov_b32 s8, 0x16180800
	s_nop 0
	v_addc_co_u32_e32 v25, vcc, 0, v5, vcc
	s_waitcnt lgkmcnt(4)
	v_cvt_pk_bf16_f32 v1, v10, v12
	s_waitcnt lgkmcnt(2)
	v_cvt_pk_bf16_f32 v2, v14, v16
	s_waitcnt lgkmcnt(0)
	v_cvt_pk_bf16_f32 v3, v18, v20
	v_add_co_u32_e32 v10, vcc, s8, v4
	global_store_dwordx4 v[24:25], v[0:3], off nt
	s_mov_b32 s8, 0x16181000
	s_nop 0
	v_cvt_pk_bf16_f32 v0, v7, v9
	v_cvt_pk_bf16_f32 v1, v11, v13
	v_cvt_pk_bf16_f32 v2, v15, v17
	v_cvt_pk_bf16_f32 v3, v19, v21
	v_addc_co_u32_e32 v11, vcc, 0, v5, vcc
	global_store_dwordx4 v[10:11], v[0:3], off nt
	ds_read2_b32 v[10:11], v22 offset0:96 offset1:112
	ds_read2_b32 v[12:13], v22 offset0:228 offset1:244
	v_add_u32_e32 v2, 0xa00, v22
	v_add_u32_e32 v3, 0xe00, v22
	ds_read2_b32 v[14:15], v23 offset0:104 offset1:120
	ds_read2_b32 v[16:17], v23 offset0:236 offset1:252
	ds_read2_b32 v[8:9], v8 offset0:112 offset1:128
	ds_read2_b32 v[18:19], v2 offset0:116 offset1:132
	ds_read2_b32 v[6:7], v6 offset0:120 offset1:136
	ds_read2_b32 v[20:21], v3 offset0:124 offset1:140
	v_add_co_u32_e32 v22, vcc, s8, v4
	s_waitcnt lgkmcnt(6)
	v_cvt_pk_bf16_f32 v0, v10, v12
	v_addc_co_u32_e32 v23, vcc, 0, v5, vcc
	s_waitcnt lgkmcnt(4)
	v_cvt_pk_bf16_f32 v1, v14, v16
	s_waitcnt lgkmcnt(2)
	v_cvt_pk_bf16_f32 v2, v8, v18
	s_waitcnt lgkmcnt(0)
	v_cvt_pk_bf16_f32 v3, v6, v20
	v_add_co_u32_e32 v4, vcc, 0x16181800, v4
	global_store_dwordx4 v[22:23], v[0:3], off nt
	s_nop 0
	v_addc_co_u32_e32 v5, vcc, 0, v5, vcc
	v_cvt_pk_bf16_f32 v0, v11, v13
	v_cvt_pk_bf16_f32 v1, v15, v17
	v_cvt_pk_bf16_f32 v2, v9, v19
	v_cvt_pk_bf16_f32 v3, v7, v21
	global_store_dwordx4 v[4:5], v[0:3], off nt

; DI int tid() { int t = threadIdx.x; asm volatile("" : "+v"(t)); return t; }
; DI int crow(int r, int h) { return (r & 3) + 8 * (r >> 2) + 4 * h; }
; DI float* stage_tile(const f32x16 (&acc)[2][2], const float* rs, char* smem) {
;     const int tt = tid(), lane = tt & 63, w = __builtin_amdgcn_readfirstlane(tt >> 6), wm = w >> 1, wn = w & 1, l32 = lane & 31, h = lane >> 5;
;     float* stg = (float*)smem;
; #pragma unroll
;     for (int i = 0; i < 2; ++i)
; #pragma unroll
;         for (int j = 0; j < 2; ++j)
; #pragma unroll
;             for (int r = 0; r < 16; ++r) {
;                 const int row = wm * 64 + i * 32 + crow(r, h);
;                 stg[row * 132 + wn * 64 + j * 32 + l32] = rs ? acc[i][j][r] * rs[row] : acc[i][j][r];
;             }
;     __syncthreads();
;     return stg;
; }
; DI void ph_qkv(KP p, int l, char* smem) {
;     ...
;             gemm_tile<1>((const bf16_t*)(p->ws + OFF_HQ), QL, rt * 128, 0, TOK, (const bf16_t*)(p->ws + OFF_WUQ) + ((size_t)l * 768 + ct * 128) * QL, QL, QL, smem, acc);
;             const float* stg = stage_tile(acc, (const float*)(smem + RS_OFF), smem);
.LBB0_212:
	s_or_b64 exec, exec, s[16:17]
	v_mov_b32_e32 v32, v182
	s_waitcnt lgkmcnt(0)
	s_barrier
	s_nop 0
	v_readfirstlane_b32 s9, v32
	s_ashr_i32 s8, s9, 1
	v_lshrrev_b32_e32 v33, 3, v32
	s_and_b32 s10, s8, 0xffffffc0
	v_and_b32_e32 v33, 4, v33
	v_or_b32_e32 v34, s10, v33
	s_add_i32 s8, 0, 0x12000
	v_lshl_add_u32 v68, v34, 2, s8
	v_and_b32_e32 v32, 31, v32
	v_and_or_b32 v32, s9, 64, v32
	v_mul_lo_u32 v34, v34, s82
	v_lshlrev_b32_e32 v32, 2, v32
	v_add3_u32 v34, 0, v34, v32
	ds_read_b128 v[70:73], v68
	ds_read_b128 v[74:77], v68 offset:32
	ds_read_b128 v[78:81], v68 offset:64
	ds_read_b128 v[82:85], v68 offset:96
	s_waitcnt lgkmcnt(0)
	v_mul_f32_e32 v52, v52, v70
	v_mul_f32_e32 v53, v53, v71
	v_mul_f32_e32 v54, v54, v72
	v_mul_f32_e32 v55, v55, v73
	v_mul_f32_e32 v56, v56, v74
	v_mul_f32_e32 v57, v57, v75
	v_mul_f32_e32 v58, v58, v76
	v_mul_f32_e32 v59, v59, v77
	v_mul_f32_e32 v60, v60, v78
	v_mul_f32_e32 v61, v61, v79
	v_mul_f32_e32 v62, v62, v80
	v_mul_f32_e32 v63, v63, v81
	v_mul_f32_e32 v64, v64, v82
	v_mul_f32_e32 v65, v65, v83
	v_mul_f32_e32 v66, v66, v84
	v_mul_f32_e32 v67, v67, v85
	v_mul_f32_e32 v36, v36, v70
	v_mul_f32_e32 v37, v37, v71
	v_mul_f32_e32 v38, v38, v72
	v_mul_f32_e32 v39, v39, v73
	v_mul_f32_e32 v40, v40, v74
	v_mul_f32_e32 v41, v41, v75
	v_mul_f32_e32 v42, v42, v76
	v_mul_f32_e32 v43, v43, v77
	v_mul_f32_e32 v44, v44, v78
	v_mul_f32_e32 v45, v45, v79
	v_mul_f32_e32 v46, v46, v80
	v_mul_f32_e32 v47, v47, v81
	v_mul_f32_e32 v48, v48, v82
	v_mul_f32_e32 v49, v49, v83
	v_mul_f32_e32 v50, v50, v84
	v_mul_f32_e32 v51, v51, v85
	ds_read_b128 v[70:73], v68 offset:128
	ds_read_b128 v[74:77], v68 offset:160
	ds_read_b128 v[78:81], v68 offset:192
	ds_read_b128 v[82:85], v68 offset:224
	ds_write2_b32 v34, v52, v53 offset1:132
	v_add_u32_e32 v86, 1056, v34
	ds_write2_b32 v86, v54, v55 offset1:132
	v_add_u32_e32 v86, 4224, v34
	ds_write2_b32 v86, v56, v57 offset1:132
	v_add_u32_e32 v86, 5280, v34
	ds_write2_b32 v86, v58, v59 offset1:132
	v_add_u32_e32 v86, 8448, v34
	ds_write2_b32 v86, v60, v61 offset1:132
	v_add_u32_e32 v86, 9504, v34
	ds_write2_b32 v86, v62, v63 offset1:132
	v_add_u32_e32 v86, 12672, v34
	ds_write2_b32 v86, v64, v65 offset1:132
	v_add_u32_e32 v86, 13728, v34
	ds_write2_b32 v86, v66, v67 offset1:132
	v_add_u32_e32 v86, 128, v34
	ds_write2_b32 v86, v36, v37 offset1:132
	v_add_u32_e32 v86, 1184, v34
	ds_write2_b32 v86, v38, v39 offset1:132
	v_add_u32_e32 v86, 4352, v34
	ds_write2_b32 v86, v40, v41 offset1:132
	v_add_u32_e32 v86, 5408, v34
	ds_write2_b32 v86, v42, v43 offset1:132
	v_add_u32_e32 v86, 8576, v34
	ds_write2_b32 v86, v44, v45 offset1:132
	v_add_u32_e32 v86, 9632, v34
	ds_write2_b32 v86, v46, v47 offset1:132
	v_add_u32_e32 v86, 12800, v34
	ds_write2_b32 v86, v48, v49 offset1:132
	v_add_u32_e32 v86, 13856, v34
	ds_write2_b32 v86, v50, v51 offset1:132
	s_waitcnt lgkmcnt(0)
	v_mul_f32_e32 v16, v16, v70
	v_mul_f32_e32 v17, v17, v71
	v_mul_f32_e32 v18, v18, v72
	v_mul_f32_e32 v19, v19, v73
	v_mul_f32_e32 v20, v20, v74
	v_mul_f32_e32 v21, v21, v75
	v_mul_f32_e32 v22, v22, v76
	v_mul_f32_e32 v23, v23, v77
	v_mul_f32_e32 v24, v24, v78
	v_mul_f32_e32 v25, v25, v79
	v_mul_f32_e32 v26, v26, v80
	v_mul_f32_e32 v27, v27, v81
	v_mul_f32_e32 v28, v28, v82
	v_mul_f32_e32 v29, v29, v83
	v_mul_f32_e32 v30, v30, v84
	v_mul_f32_e32 v31, v31, v85
	v_mul_f32_e32 v0, v0, v70
	v_mul_f32_e32 v1, v1, v71
	v_mul_f32_e32 v2, v2, v72
	v_mul_f32_e32 v3, v3, v73
	v_mul_f32_e32 v4, v4, v74
	v_mul_f32_e32 v5, v5, v75
	v_mul_f32_e32 v6, v6, v76
	v_mul_f32_e32 v7, v7, v77
	v_mul_f32_e32 v8, v8, v78
	v_mul_f32_e32 v9, v9, v79
	v_mul_f32_e32 v10, v10, v80
	v_mul_f32_e32 v11, v11, v81
	v_mul_f32_e32 v12, v12, v82
	v_mul_f32_e32 v13, v13, v83
	v_mul_f32_e32 v14, v14, v84
	v_mul_f32_e32 v15, v15, v85
	v_add_u32_e32 v86, 16896, v34
	ds_write2_b32 v86, v16, v17 offset1:132
	v_add_u32_e32 v86, 17952, v34
	ds_write2_b32 v86, v18, v19 offset1:132
	v_add_u32_e32 v86, 21120, v34
	ds_write2_b32 v86, v20, v21 offset1:132
	v_add_u32_e32 v86, 22176, v34
	ds_write2_b32 v86, v22, v23 offset1:132
	v_add_u32_e32 v86, 25344, v34
	ds_write2_b32 v86, v24, v25 offset1:132
	v_add_u32_e32 v86, 26400, v34
	ds_write2_b32 v86, v26, v27 offset1:132
	v_add_u32_e32 v86, 29568, v34
	ds_write2_b32 v86, v28, v29 offset1:132
	v_add_u32_e32 v86, 30624, v34
	ds_write2_b32 v86, v30, v31 offset1:132
	v_add_u32_e32 v86, 17024, v34
	ds_write2_b32 v86, v0, v1 offset1:132
	v_add_u32_e32 v86, 18080, v34
	ds_write2_b32 v86, v2, v3 offset1:132
	v_add_u32_e32 v86, 21248, v34
	ds_write2_b32 v86, v4, v5 offset1:132
	v_add_u32_e32 v86, 22304, v34
	ds_write2_b32 v86, v6, v7 offset1:132
	v_add_u32_e32 v86, 25472, v34
	ds_write2_b32 v86, v8, v9 offset1:132
	v_add_u32_e32 v86, 26528, v34
	ds_write2_b32 v86, v10, v11 offset1:132
	v_add_u32_e32 v86, 29696, v34
	ds_write2_b32 v86, v12, v13 offset1:132
	v_add_u32_e32 v86, 30752, v34
	ds_write2_b32 v86, v14, v15 offset1:132
	v_mov_b32_e32 v1, v182
	s_waitcnt lgkmcnt(0)
	s_barrier
; DI int tid() { int t = threadIdx.x; asm volatile("" : "+v"(t)); return t; }
; DI void ph_qkv(KP p, int l, char* smem) {
;     ...
;             const int tt = tid(), c8 = tt & 15, n8 = ct * 128 + c8 * 8, head = n8 / 96, w0 = n8 - head * 96;
;             const float qs = 0.10206207261596575f * LOG2E;
; #pragma unroll
;             for (int i = 0; i < 8; ++i) {
;                 const int row = (tt >> 4) + 16 * i, tok = rt * 128 + row;
;                 float4 lo = *(const float4*)(stg + row * 132 + c8 * 8), hi = *(const float4*)(stg + row * 132 + c8 * 8 + 4);
;                 if (w0 >= 64) {
;                     const int c = w0 - 64, pc = c8 * 8 + (c < 16 ? 16 : -16);
;                     const float4 plo = *(const float4*)(stg + row * 132 + pc), phi = *(const float4*)(stg + row * 132 + pc + 4);
;                     rope8(lo, hi, plo, phi, (const float*)(p->ws + OFF_COS) + (size_t)tok * 16, (const float*)(p->ws + OFF_SIN) + (size_t)tok * 16, c);
;                 }
	s_nop 0
	v_lshlrev_b32_e32 v0, 3, v1
	v_and_b32_e32 v25, 0x78, v0
	v_ashrrev_i32_e32 v26, 4, v1
	v_or_b32_e32 v10, s7, v25
	v_and_b32_e32 v9, 8, v0
	v_mul_lo_u32 v0, v26, s82
	v_lshlrev_b32_e32 v1, 2, v25
	v_mul_hi_i32 v2, v10, s87
	v_add3_u32 v8, 0, v0, v1
	v_lshrrev_b32_e32 v11, 31, v2
	v_ashrrev_i32_e32 v12, 4, v2
	ds_read_b128 v[4:7], v8
	ds_read_b128 v[0:3], v8 offset:16
	v_add_u32_e32 v22, v12, v11
	s_movk_i32 s7, 0xffa0
	v_mad_u64_u32 v[16:17], s[8:9], v22, s7, v[10:11]
	s_movk_i32 s7, 0x50
	v_cmp_gt_u32_e32 vcc, s7, v16
	v_and_b32_e32 v10, 0x7ffffff0, v16
	v_add_u32_e32 v18, s6, v26
	v_cndmask_b32_e64 v24, -16, 16, vcc
	v_cmp_eq_u32_e32 vcc, 64, v10
	v_cmp_lt_i32_e64 s[42:43], 63, v16
	v_lshlrev_b32_e32 v34, 2, v9
	v_cndmask_b32_e64 v23, 1.0, -1.0, vcc
	s_and_saveexec_b64 s[16:17], s[42:43]
	s_cbranch_execz .LBB0_214
	v_lshl_add_u32 v8, v24, 2, v8
	v_ashrrev_i32_e32 v19, 31, v18
	ds_read_b128 v[28:31], v8
	ds_read_b128 v[36:39], v8 offset:16
	v_lshlrev_b64 v[8:9], 6, v[18:19]
	v_lshl_add_u64 v[8:9], s[14:15], 0, v[8:9]
	v_lshl_add_u64 v[12:13], v[8:9], 0, v[34:35]
	s_mov_b32 s7, 0x7980000
	s_mov_b64 s[8:9], 0x7980000
	v_add_co_u32_e32 v10, vcc, s7, v12
	v_lshl_add_u64 v[8:9], v[12:13], 0, s[8:9]
	s_nop 0
	v_addc_co_u32_e32 v11, vcc, 0, v13, vcc
	s_mov_b64 s[8:9], 0x7d80000
	s_mov_b32 s7, 0x7d80000
	v_lshl_add_u64 v[14:15], v[12:13], 0, s[8:9]
	v_add_co_u32_e32 v12, vcc, s7, v12
	global_load_dwordx4 v[40:43], v[10:11], off
	s_nop 0
	global_load_dwordx4 v[8:11], v[8:9], off offset:16
	v_addc_co_u32_e32 v13, vcc, 0, v13, vcc
	global_load_dwordx4 v[44:47], v[12:13], off
	s_nop 0
	global_load_dwordx4 v[12:15], v[14:15], off offset:16
	s_waitcnt lgkmcnt(1)
	v_mul_f32_e32 v17, v23, v28
	v_mul_f32_e32 v29, v23, v29
	v_mov_b32_e32 v28, v5
	s_waitcnt vmcnt(3)
	v_mul_f32_e32 v4, v4, v40
	v_mul_f32_e32 v6, v6, v42
	s_waitcnt vmcnt(2)
	v_mul_f32_e32 v0, v0, v8
	s_waitcnt vmcnt(1)
	v_mul_f32_e32 v20, v17, v44
	v_mov_b32_e32 v44, v41
	v_pk_mul_f32 v[28:29], v[28:29], v[44:45]
	v_mul_f32_e32 v17, v23, v30
	v_mov_b32_e32 v5, v28
	v_mov_b32_e32 v21, v29
	v_pk_add_f32 v[4:5], v[4:5], v[20:21]
	v_mul_f32_e32 v20, v17, v46
	v_mul_f32_e32 v29, v23, v31
	v_mov_b32_e32 v28, v7
	v_mov_b32_e32 v46, v43
	v_pk_mul_f32 v[28:29], v[28:29], v[46:47]
	s_waitcnt lgkmcnt(0)
	v_mul_f32_e32 v8, v23, v36
	v_mov_b32_e32 v7, v28
	v_mov_b32_e32 v21, v29
	v_pk_add_f32 v[6:7], v[6:7], v[20:21]
	s_waitcnt vmcnt(0)
	v_mul_f32_e32 v8, v8, v12
	v_mul_f32_e32 v21, v23, v37
	v_mov_b32_e32 v20, v1
	v_mov_b32_e32 v12, v9
	v_pk_mul_f32 v[12:13], v[20:21], v[12:13]
	v_mul_f32_e32 v2, v2, v10
	v_mov_b32_e32 v1, v12
	v_mov_b32_e32 v9, v13
	v_pk_add_f32 v[0:1], v[0:1], v[8:9]
	v_mul_f32_e32 v8, v23, v38
	v_mul_f32_e32 v8, v8, v14
	v_mul_f32_e32 v13, v23, v39
	v_mov_b32_e32 v12, v3
	v_mov_b32_e32 v14, v11
	v_pk_mul_f32 v[10:11], v[12:13], v[14:15]
	s_nop 0
	v_mov_b32_e32 v3, v10
	v_mov_b32_e32 v9, v11
	v_pk_add_f32 v[2:3], v[2:3], v[8:9]

; DI int tid() { int t = threadIdx.x; asm volatile("" : "+v"(t)); return t; }
; DI int crow(int r, int h) { return (r & 3) + 8 * (r >> 2) + 4 * h; }
; DI float* stage_tile(const f32x16 (&acc)[2][2], const float* rs, char* smem) {
;     const int tt = tid(), lane = tt & 63, w = __builtin_amdgcn_readfirstlane(tt >> 6), wm = w >> 1, wn = w & 1, l32 = lane & 31, h = lane >> 5;
;     float* stg = (float*)smem;
; #pragma unroll
;     for (int i = 0; i < 2; ++i)
; #pragma unroll
;         for (int j = 0; j < 2; ++j)
; #pragma unroll
;             for (int r = 0; r < 16; ++r) {
;                 const int row = wm * 64 + i * 32 + crow(r, h);
;                 stg[row * 132 + wn * 64 + j * 32 + l32] = rs ? acc[i][j][r] * rs[row] : acc[i][j][r];
;             }
;     __syncthreads();
;     return stg;
; }
; DI void ph_in(KP p, int l, const float* xin, char* smem) {
;     ...
;         rs_finish(rsp, rt * 128, smem);
;         const float* stg = stage_tile(acc, (const float*)(smem + RS_OFF), smem);
.LBB0_244:
	s_or_b64 exec, exec, s[14:15]
	v_mov_b32_e32 v32, v182
	s_waitcnt lgkmcnt(0)
	s_barrier
	s_nop 0
	s_waitcnt vmcnt(0)
	v_readfirstlane_b32 s12, v32
	v_and_b32_e32 v33, 31, v32
	s_ashr_i32 s13, s12, 1
	v_lshrrev_b32_e32 v32, 3, v32
	s_andn2_b32 s13, s13, 63
	v_and_b32_e32 v68, 4, v32
	v_and_or_b32 v32, s12, 64, v33
	v_or_b32_e32 v33, s13, v68
	s_add_i32 s12, 0, 0x12000
	v_lshl_add_u32 v69, v33, 2, s12
	v_mul_lo_u32 v33, v33, s82
	v_lshlrev_b32_e32 v32, 2, v32
	v_add3_u32 v34, 0, v33, v32
	ds_read_b128 v[70:73], v69
	ds_read_b128 v[74:77], v69 offset:32
	ds_read_b128 v[78:81], v69 offset:64
	ds_read_b128 v[82:85], v69 offset:96
	s_waitcnt lgkmcnt(0)
	v_mul_f32_e32 v0, v0, v70
	v_mul_f32_e32 v1, v1, v71
	v_mul_f32_e32 v2, v2, v72
	v_mul_f32_e32 v3, v3, v73
	v_mul_f32_e32 v4, v4, v74
	v_mul_f32_e32 v5, v5, v75
	v_mul_f32_e32 v6, v6, v76
	v_mul_f32_e32 v7, v7, v77
	v_mul_f32_e32 v8, v8, v78
	v_mul_f32_e32 v9, v9, v79
	v_mul_f32_e32 v10, v10, v80
	v_mul_f32_e32 v11, v11, v81
	v_mul_f32_e32 v12, v12, v82
	v_mul_f32_e32 v13, v13, v83
	v_mul_f32_e32 v14, v14, v84
	v_mul_f32_e32 v15, v15, v85
	v_mul_f32_e32 v52, v52, v70
	v_mul_f32_e32 v53, v53, v71
	v_mul_f32_e32 v54, v54, v72
	v_mul_f32_e32 v55, v55, v73
	v_mul_f32_e32 v56, v56, v74
	v_mul_f32_e32 v57, v57, v75
	v_mul_f32_e32 v58, v58, v76
	v_mul_f32_e32 v59, v59, v77
	v_mul_f32_e32 v60, v60, v78
	v_mul_f32_e32 v61, v61, v79
	v_mul_f32_e32 v62, v62, v80
	v_mul_f32_e32 v63, v63, v81
	v_mul_f32_e32 v64, v64, v82
	v_mul_f32_e32 v65, v65, v83
	v_mul_f32_e32 v66, v66, v84
	v_mul_f32_e32 v67, v67, v85
	ds_read_b128 v[70:73], v69 offset:128
	ds_read_b128 v[74:77], v69 offset:160
	ds_read_b128 v[78:81], v69 offset:192
	ds_read_b128 v[82:85], v69 offset:224
	ds_write2_b32 v34, v0, v1 offset1:132
	v_add_u32_e32 v86, 1056, v34
	ds_write2_b32 v86, v2, v3 offset1:132
	v_add_u32_e32 v86, 4224, v34
	ds_write2_b32 v86, v4, v5 offset1:132
	v_add_u32_e32 v86, 5280, v34
	ds_write2_b32 v86, v6, v7 offset1:132
	v_add_u32_e32 v86, 8448, v34
	ds_write2_b32 v86, v8, v9 offset1:132
	v_add_u32_e32 v86, 9504, v34
	ds_write2_b32 v86, v10, v11 offset1:132
	v_add_u32_e32 v86, 12672, v34
	ds_write2_b32 v86, v12, v13 offset1:132
	v_add_u32_e32 v86, 13728, v34
	ds_write2_b32 v86, v14, v15 offset1:132
	v_add_u32_e32 v86, 128, v34
	ds_write2_b32 v86, v52, v53 offset1:132
	v_add_u32_e32 v86, 1184, v34
	ds_write2_b32 v86, v54, v55 offset1:132
	v_add_u32_e32 v86, 4352, v34
	ds_write2_b32 v86, v56, v57 offset1:132
	v_add_u32_e32 v86, 5408, v34
	ds_write2_b32 v86, v58, v59 offset1:132
	v_add_u32_e32 v86, 8576, v34
	ds_write2_b32 v86, v60, v61 offset1:132
	v_add_u32_e32 v86, 9632, v34
	ds_write2_b32 v86, v62, v63 offset1:132
	v_add_u32_e32 v86, 12800, v34
	ds_write2_b32 v86, v64, v65 offset1:132
	v_add_u32_e32 v86, 13856, v34
	ds_write2_b32 v86, v66, v67 offset1:132
	s_waitcnt lgkmcnt(0)
	v_mul_f32_e32 v36, v36, v70
	v_mul_f32_e32 v37, v37, v71
	v_mul_f32_e32 v38, v38, v72
	v_mul_f32_e32 v39, v39, v73
	v_mul_f32_e32 v40, v40, v74
	v_mul_f32_e32 v41, v41, v75
	v_mul_f32_e32 v42, v42, v76
	v_mul_f32_e32 v43, v43, v77
	v_mul_f32_e32 v44, v44, v78
	v_mul_f32_e32 v45, v45, v79
	v_mul_f32_e32 v46, v46, v80
	v_mul_f32_e32 v47, v47, v81
	v_mul_f32_e32 v48, v48, v82
	v_mul_f32_e32 v49, v49, v83
	v_mul_f32_e32 v50, v50, v84
	v_mul_f32_e32 v51, v51, v85
	v_mul_f32_e32 v16, v16, v70
	v_mul_f32_e32 v17, v17, v71
	v_mul_f32_e32 v18, v18, v72
	v_mul_f32_e32 v19, v19, v73
	v_mul_f32_e32 v20, v20, v74
	v_mul_f32_e32 v21, v21, v75
	v_mul_f32_e32 v22, v22, v76
	v_mul_f32_e32 v23, v23, v77
	v_mul_f32_e32 v24, v24, v78
	v_mul_f32_e32 v25, v25, v79
	v_mul_f32_e32 v26, v26, v80
	v_mul_f32_e32 v27, v27, v81
	v_mul_f32_e32 v28, v28, v82
	v_mul_f32_e32 v29, v29, v83
	v_mul_f32_e32 v30, v30, v84
	v_mul_f32_e32 v31, v31, v85
	v_add_u32_e32 v86, 16896, v34
	ds_write2_b32 v86, v36, v37 offset1:132
	v_add_u32_e32 v86, 17952, v34
	ds_write2_b32 v86, v38, v39 offset1:132
	v_add_u32_e32 v86, 21120, v34
	ds_write2_b32 v86, v40, v41 offset1:132
	v_add_u32_e32 v86, 22176, v34
	ds_write2_b32 v86, v42, v43 offset1:132
	v_add_u32_e32 v86, 25344, v34
	ds_write2_b32 v86, v44, v45 offset1:132
	v_add_u32_e32 v86, 26400, v34
	ds_write2_b32 v86, v46, v47 offset1:132
	v_add_u32_e32 v86, 29568, v34
	ds_write2_b32 v86, v48, v49 offset1:132
	v_add_u32_e32 v86, 30624, v34
	ds_write2_b32 v86, v50, v51 offset1:132
	v_add_u32_e32 v86, 17024, v34
	ds_write2_b32 v86, v16, v17 offset1:132
	v_add_u32_e32 v86, 18080, v34
	ds_write2_b32 v86, v18, v19 offset1:132
	v_add_u32_e32 v86, 21248, v34
	ds_write2_b32 v86, v20, v21 offset1:132
	v_add_u32_e32 v86, 22304, v34
	ds_write2_b32 v86, v22, v23 offset1:132
	v_add_u32_e32 v86, 25472, v34
	ds_write2_b32 v86, v24, v25 offset1:132
	v_add_u32_e32 v86, 26528, v34
	ds_write2_b32 v86, v26, v27 offset1:132
	v_add_u32_e32 v86, 29696, v34
	ds_write2_b32 v86, v28, v29 offset1:132
	v_add_u32_e32 v86, 30752, v34
	ds_write2_b32 v86, v30, v31 offset1:132
	v_mov_b32_e32 v1, v182
	s_waitcnt lgkmcnt(0)
	s_barrier
; DI int tid() { int t = threadIdx.x; asm volatile("" : "+v"(t)); return t; }
; DI void st_nt16(void* p, const uint4& v) { u32x4 t = {v.x, v.y, v.z, v.w}; __builtin_nontemporal_store(t, (u32x4*)p); }
; DI uint4 pack8(const float4& a, const float4& b) { uint4 o; o.x = pack2(a.x, a.y); o.y = pack2(a.z, a.w); o.z = pack2(b.x, b.y); o.w = pack2(b.z, b.w); return o; }
; DI float4 gelu4(const float4& a) { float4 o; o.x = gelu_tanh(a.x); o.y = gelu_tanh(a.y); o.z = gelu_tanh(a.z); o.w = gelu_tanh(a.w); return o; }
; DI void ph_in(KP p, int l, const float* xin, char* smem) {
;     ...
;         const int tt = tid(), c8 = tt & 15, nb = ct * 128 + c8 * 8;
;         if (nb < INC) {
; #pragma unroll
;             for (int i = 0; i < 8; ++i) {
;                 const int row = (tt >> 4) + 16 * i, tok = rt * 128 + row;
;                 float4 lo = *(const float4*)(stg + row * 132 + c8 * 8), hi = *(const float4*)(stg + row * 132 + c8 * 8 + 4);
;                 if (nb < 256) st_nt16((bf16_t*)(p->ws + OFF_HQ) + (size_t)tok * 256 + nb, pack8(lo, hi));
;                 else if (nb < 384) st_nt16((bf16_t*)(p->ws + OFF_HKV) + (size_t)tok * 128 + (nb - 256), pack8(lo, hi));
;                 else if (nb < 416) {
;                     const int c = nb - 384, pc = c8 * 8 + (c < 16 ? 16 : -16);
;                     const float4 plo = *(const float4*)(stg + row * 132 + pc), phi = *(const float4*)(stg + row * 132 + pc + 4);
;                     rope8(lo, hi, plo, phi, (const float*)(p->ws + OFF_COS) + (size_t)tok * 16, (const float*)(p->ws + OFF_SIN) + (size_t)tok * 16, c);
;                     const uint4 ov = pack8(lo, hi);
;                     const int b = tok >> 13, sx = tok & 8191;
;                     bf16_t* dst = (bf16_t*)(p->ws + OFF_K) + (((size_t)(b * 8)) * SEQ + sx) * 96 + 64 + c;
; #pragma unroll
;                     for (int hd = 0; hd < 8; ++hd) st_nt16(dst + (size_t)hd * SEQ * 96, ov);
;                 } else if (nb < 928) st_nt16((bf16_t*)(p->ws + OFF_U) + (size_t)tok * 512 + (nb - 416), pack8(gelu4(lo), gelu4(hi)));
;                 else st_nt16((bf16_t*)(p->ws + OFF_V) + (size_t)tok * 512 + (nb - 928), pack8(gelu4(lo), gelu4(hi)));
	s_nop 0
	v_lshlrev_b32_e32 v0, 3, v1
	v_and_b32_e32 v25, 0x78, v0
	v_or_b32_e32 v16, s10, v25
	s_movk_i32 s10, 0x5a0
	v_cmp_gt_i32_e32 vcc, s10, v16
	s_and_saveexec_b64 s[14:15], vcc
	s_cbranch_execz .LBB0_233
	v_ashrrev_i32_e32 v26, 4, v1
	v_and_b32_e32 v15, 8, v0
	v_mul_lo_u32 v0, v26, s82
	v_add_u32_e32 v22, 0, v0
	s_cmpk_gt_u32 s9, 0x17f
	s_movk_i32 s9, 0x19f
	v_lshl_add_u32 v8, v25, 2, v22
	v_cmp_lt_u32_e64 s[44:45], s9, v16
	s_movk_i32 s9, 0x39f
	ds_read_b128 v[4:7], v8
	ds_read_b128 v[0:3], v8 offset:16
	v_cmp_lt_u32_e64 s[42:43], s9, v16
	s_movk_i32 s9, 0x190
	v_add_u32_e32 v12, 0xfffffe80, v16
	v_cmp_gt_u32_e32 vcc, s9, v16
	s_movk_i32 s10, 0xff
	v_cmp_lt_i32_e64 s[46:47], s10, v16
	v_cndmask_b32_e64 v24, -16, 16, vcc
	v_cmp_gt_u32_e32 vcc, 16, v12
	s_cselect_b64 s[16:17], -1, 0
	v_mov_b32_e32 v34, v16
	v_cndmask_b32_e64 v14, 1.0, -1.0, vcc
	v_mov_b32_e32 v13, v35
	v_add_u32_e32 v18, s8, v26
	s_and_saveexec_b64 s[10:11], s[46:47]
	s_xor_b64 s[36:37], exec, s[10:11]
	s_cbranch_execz .LBB0_258
	s_mov_b64 s[40:41], -1
	s_and_b64 vcc, exec, s[16:17]
	s_cbranch_vccz .LBB0_256
	s_and_saveexec_b64 s[10:11], s[44:45]
	s_xor_b64 s[40:41], exec, s[10:11]
	s_cbranch_execz .LBB0_253
	v_ashrrev_i32_e32 v19, 31, v18
	s_waitcnt lgkmcnt(0)
	v_mul_f32_e32 v17, 0x3d372713, v0
	v_lshlrev_b64 v[8:9], 10, v[18:19]
	v_mul_f32_e32 v17, v0, v17
	v_mul_f32_e32 v19, 0x3d372713, v1
	v_mul_f32_e32 v10, 0x3d372713, v4
	v_mul_f32_e32 v11, 0x3d372713, v5
	v_fma_f32 v17, v0, v17, v0
	v_mul_f32_e32 v19, v1, v19
	v_mul_f32_e32 v10, v4, v10
	v_mul_f32_e32 v11, v5, v11
	v_mul_f32_e32 v17, 0x3f4c422a, v17
	v_fma_f32 v19, v1, v19, v1
	v_fma_f32 v10, v4, v10, v4
	v_fma_f32 v11, v5, v11, v5
	v_mul_f32_e32 v17, 0xc038aa3b, v17
	v_mul_f32_e32 v19, 0x3f4c422a, v19
	v_mul_f32_e32 v10, 0x3f4c422a, v10
	v_mul_f32_e32 v11, 0x3f4c422a, v11
	v_exp_f32_e32 v17, v17
	v_mul_f32_e32 v19, 0xc038aa3b, v19
	v_mul_f32_e32 v10, 0xc038aa3b, v10
	v_mul_f32_e32 v11, 0xc038aa3b, v11
	v_exp_f32_e32 v19, v19
	v_exp_f32_e32 v10, v10
	v_exp_f32_e32 v11, v11
	v_add_f32_e32 v17, 1.0, v17
	v_lshl_add_u64 v[8:9], s[18:19], 0, v[8:9]
	v_rcp_f32_e32 v28, v17
	v_add_f32_e32 v17, 1.0, v19
	v_mul_f32_e32 v19, 0x3d372713, v2
	v_lshl_add_u64 v[20:21], v[34:35], 1, v[8:9]
	v_add_f32_e32 v8, 1.0, v10
	v_add_f32_e32 v9, 1.0, v11
	v_mul_f32_e32 v10, 0x3d372713, v6
	v_mul_f32_e32 v11, 0x3d372713, v7
	v_mul_f32_e32 v19, v2, v19
	v_mul_f32_e32 v23, 0x3d372713, v3
	v_mul_f32_e32 v10, v6, v10
	v_mul_f32_e32 v11, v7, v11
	v_fma_f32 v19, v2, v19, v2
	v_mul_f32_e32 v23, v3, v23
	v_fma_f32 v10, v6, v10, v6
	v_fma_f32 v11, v7, v11, v7
	v_mul_f32_e32 v19, 0x3f4c422a, v19
	v_fma_f32 v23, v3, v23, v3
	v_mul_f32_e32 v10, 0x3f4c422a, v10
	v_mul_f32_e32 v11, 0x3f4c422a, v11
	v_mul_f32_e32 v19, 0xc038aa3b, v19
	v_mul_f32_e32 v23, 0x3f4c422a, v23
	v_mul_f32_e32 v10, 0xc038aa3b, v10
	v_mul_f32_e32 v11, 0xc038aa3b, v11
	v_exp_f32_e32 v19, v19
	v_mul_f32_e32 v23, 0xc038aa3b, v23
	v_exp_f32_e32 v10, v10
	v_exp_f32_e32 v11, v11
	v_exp_f32_e32 v23, v23
	v_rcp_f32_e32 v29, v17
	v_add_f32_e32 v17, 1.0, v19
	v_add_f32_e32 v10, 1.0, v10
	v_add_f32_e32 v11, 1.0, v11
	v_rcp_f32_e32 v30, v17
	v_add_f32_e32 v17, 1.0, v23
	v_rcp_f32_e32 v8, v8
	v_rcp_f32_e32 v9, v9
	v_rcp_f32_e32 v10, v10
	v_rcp_f32_e32 v11, v11
	v_rcp_f32_e32 v31, v17
	v_pk_mul_f32 v[8:9], v[4:5], v[8:9]
	v_pk_mul_f32 v[28:29], v[0:1], v[28:29]
	v_pk_mul_f32 v[10:11], v[6:7], v[10:11]
	v_pk_mul_f32 v[30:31], v[2:3], v[30:31]
	v_cvt_pk_bf16_f32 v8, v8, v9
	v_cvt_pk_bf16_f32 v9, v10, v11
	v_cvt_pk_bf16_f32 v10, v28, v29
	v_cvt_pk_bf16_f32 v11, v30, v31
	s_and_saveexec_b64 s[10:11], s[42:43]
	s_xor_b64 s[48:49], exec, s[10:11]
	s_cbranch_execz .LBB0_250
	v_add_co_u32_e32 v20, vcc, 0x1e17f000, v20
	s_nop 1
	v_addc_co_u32_e32 v21, vcc, 0, v21, vcc
	global_store_dwordx4 v[20:21], v[8:11], off offset:2240 nt
